# v35 + LRU item-end LDS chains de-serialised (LRU0 chunk-summary combine reads issued together; LRU1 segment prefix made branch-free with hoisted reads)
# baseline (speedup 1.0000x reference)
; __device__ __forceinline__ bf16_t f2bf(float f) { return (bf16_t)(cvt_pk_bf16(f, 0.f) & 0xffffu); }
; __device__ __forceinline__ float bf2f(bf16_t b) { return __uint_as_float(((unsigned)b) << 16); }
; __device__ __forceinline__ float sigm(float x) { return __builtin_amdgcn_rcpf(1.0f + __expf(-x)); }
; template <int PASS>
; __device__ void lru_items(const Params& p, unsigned char* shm, int l) {
;     ...
;         { const int j = tid & 63;
; #pragma unroll
;           for (int i = 0; i < 8; ++i) { const int t = (tid >> 6) + 8 * i;
;               const float v = cb + bf2f(xraw[t * 64 + j]) * c0 + bf2f(xraw[(t + 1) * 64 + j]) * c1 + bf2f(xraw[(t + 2) * 64 + j]) * c2 + bf2f(xraw[(t + 3) * 64 + j]) * c3;
;               xcf[t * 65 + j] = v; xcb[t * 72 + j] = f2bf(v); } }
;         __syncthreads();
;         { const int d = w >> 2, tt = w & 3;
;           const bf16x8 a0 = *(const bf16x8*)(xcb + (tt * 16 + fr) * 72 + fq * 8), a1 = *(const bf16x8*)(xcb + (tt * 16 + fr) * 72 + 32 + fq * 8);
; #pragma unroll
;           for (int jt = 0; jt < 4; ++jt) {
;               f32x4 accr = (f32x4){0.f, 0.f, 0.f, 0.f}, acci = (f32x4){0.f, 0.f, 0.f, 0.f};
;               const bf16_t* wr_ = wt + ((d * 2 + 0) * 64 + jt * 16 + fr) * 72 + fq * 8; const bf16_t* wi_ = wt + ((d * 2 + 1) * 64 + jt * 16 + fr) * 72 + fq * 8;
;               accr = __builtin_amdgcn_mfma_f32_16x16x32_bf16(a0, *(const bf16x8*)wr_, accr, 0, 0, 0);
;               accr = __builtin_amdgcn_mfma_f32_16x16x32_bf16(a1, *(const bf16x8*)(wr_ + 32), accr, 0, 0, 0);
;               acci = __builtin_amdgcn_mfma_f32_16x16x32_bf16(a0, *(const bf16x8*)wi_, acci, 0, 0, 0);
;               acci = __builtin_amdgcn_mfma_f32_16x16x32_bf16(a1, *(const bf16x8*)(wi_ + 32), acci, 0, 0, 0);
;               const int j = jt * 16 + fr;
; #pragma unroll
;               for (int i = 0; i < 4; ++i) { const int t = tt * 16 + fq * 4 + i;
;                   const float r = sigm(accr[i] + gba[jt]), ig = sigm(acci[i] + gbx[jt]), a = __expf(r * gsp[jt]);
;                   As[(d * 64 + t) * 64 + j] = a;
;                   Bs[(d * 64 + t) * 64 + j] = sqrtf(fmaxf(1.0f - a * a, 0.f)) * ig * xcf[t * 65 + j]; }
;           } }
.LBB0_214:
	s_mov_b32 s0, 0xf800000
	v_lshrrev_b32_e32 v183, 6, v229
	v_and_b32_e32 v184, 63, v229
	v_lshlrev_b32_e32 v185, 10, v183
	v_lshl_add_u32 v185, v184, 1, v185
	ds_read_u16 v186, v185
	ds_read_u16 v187, v185 offset:128
	ds_read_u16 v188, v185 offset:256
	ds_read_u16 v189, v185 offset:384
	ds_read_u16 v190, v185 offset:512
	ds_read_u16 v191, v185 offset:640
	ds_read_u16 v192, v185 offset:768
	ds_read_u16 v193, v185 offset:896
	ds_read_u16 v194, v185 offset:1024
	ds_read_u16 v196, v185 offset:1152
	ds_read_u16 v197, v185 offset:1280
	v_mul_u32_u24_e32 v206, 0x820, v183
	v_lshl_add_u32 v206, v184, 2, v206
	v_mul_u32_u24_e32 v207, 0x480, v183
	v_lshl_add_u32 v207, v184, 1, v207
	s_waitcnt lgkmcnt(0)
	v_lshlrev_b32_e32 v186, 16, v186
	v_lshlrev_b32_e32 v187, 16, v187
	v_lshlrev_b32_e32 v188, 16, v188
	v_lshlrev_b32_e32 v189, 16, v189
	v_lshlrev_b32_e32 v190, 16, v190
	v_lshlrev_b32_e32 v191, 16, v191
	v_lshlrev_b32_e32 v192, 16, v192
	v_lshlrev_b32_e32 v193, 16, v193
	v_lshlrev_b32_e32 v194, 16, v194
	v_lshlrev_b32_e32 v196, 16, v196
	v_lshlrev_b32_e32 v197, 16, v197
	v_fma_f32 v198, v151, v186, v150
	v_fma_f32 v199, v151, v187, v150
	v_fma_f32 v200, v151, v188, v150
	v_fma_f32 v201, v151, v189, v150
	v_fma_f32 v202, v151, v190, v150
	v_fma_f32 v203, v151, v191, v150
	v_fma_f32 v204, v151, v192, v150
	v_fma_f32 v205, v151, v193, v150
	v_fmac_f32_e32 v198, v154, v187
	v_fmac_f32_e32 v199, v154, v188
	v_fmac_f32_e32 v200, v154, v189
	v_fmac_f32_e32 v201, v154, v190
	v_fmac_f32_e32 v202, v154, v191
	v_fmac_f32_e32 v203, v154, v192
	v_fmac_f32_e32 v204, v154, v193
	v_fmac_f32_e32 v205, v154, v194
	v_fmac_f32_e32 v198, v153, v188
	v_fmac_f32_e32 v199, v153, v189
	v_fmac_f32_e32 v200, v153, v190
	v_fmac_f32_e32 v201, v153, v191
	v_fmac_f32_e32 v202, v153, v192
	v_fmac_f32_e32 v203, v153, v193
	v_fmac_f32_e32 v204, v153, v194
	v_fmac_f32_e32 v205, v153, v196
	v_fmac_f32_e32 v198, v152, v189
	v_fmac_f32_e32 v199, v152, v190
	v_fmac_f32_e32 v200, v152, v191
	v_fmac_f32_e32 v201, v152, v192
	v_fmac_f32_e32 v202, v152, v193
	v_fmac_f32_e32 v203, v152, v194
	v_fmac_f32_e32 v204, v152, v196
	v_fmac_f32_e32 v205, v152, v197
	ds_write_b32 v206, v198 offset:8704
	ds_write_b32 v206, v199 offset:8964
	ds_write_b32 v206, v200 offset:9224
	ds_write_b32 v206, v201 offset:9484
	ds_write_b32 v206, v202 offset:9744
	ds_write_b32 v206, v203 offset:10004
	ds_write_b32 v206, v204 offset:10264
	ds_write_b32 v206, v205 offset:10524
	v_cvt_pk_bf16_f32 v186, v198, v1
	v_cvt_pk_bf16_f32 v187, v199, v1
	ds_write_b16 v207, v186 offset:25344
	v_cvt_pk_bf16_f32 v188, v200, v1
	ds_write_b16 v207, v187 offset:25488
	v_cvt_pk_bf16_f32 v189, v201, v1
	ds_write_b16 v207, v188 offset:25632
	v_cvt_pk_bf16_f32 v190, v202, v1
	ds_write_b16 v207, v189 offset:25776
	v_cvt_pk_bf16_f32 v191, v203, v1
	ds_write_b16 v207, v190 offset:25920
	v_cvt_pk_bf16_f32 v192, v204, v1
	ds_write_b16 v207, v191 offset:26064
	v_cvt_pk_bf16_f32 v193, v205, v1
	ds_write_b16 v207, v192 offset:26208
	ds_write_b16 v207, v193 offset:26352
	s_waitcnt lgkmcnt(0)
	s_barrier
	ds_read_b32 v186, v149 offset:8704
	ds_read_b32 v187, v149 offset:8964
	ds_read_b32 v188, v149 offset:9224
	ds_read_b32 v189, v149 offset:9484
	ds_read_b32 v190, v149 offset:8768
	ds_read_b32 v191, v149 offset:9028
	ds_read_b32 v192, v149 offset:9288
	ds_read_b32 v193, v149 offset:9548
	ds_read_b32 v194, v149 offset:8832
	ds_read_b32 v196, v149 offset:9092
	ds_read_b32 v197, v149 offset:9352
	ds_read_b32 v198, v149 offset:9612
	ds_read_b32 v199, v149 offset:8896
	ds_read_b32 v200, v149 offset:9156
	ds_read_b32 v201, v149 offset:9416
	ds_read_b32 v202, v149 offset:9676
	ds_read_b128 v[18:21], v47 offset:25344
	ds_read_b128 v[14:17], v47 offset:25408
	ds_read_b128 v[160:163], v72 offset:34560
	ds_read_b128 v[164:167], v72 offset:34624
	s_waitcnt lgkmcnt(1)
	v_mfma_f32_16x16x32_bf16 v[160:163], v[18:21], v[160:163], 0
	ds_read_b128 v[168:171], v73 offset:43840
	s_waitcnt lgkmcnt(1)
	v_mfma_f32_16x16x32_bf16 v[160:163], v[14:17], v[164:167], v[160:163]
	ds_read_b128 v[164:167], v73 offset:43776
	s_waitcnt lgkmcnt(0)
	v_mfma_f32_16x16x32_bf16 v[164:167], v[18:21], v[164:167], 0
	s_waitcnt vmcnt(9)
	s_nop 3
	v_fmamk_f32 v0, v160, 0xbfb8aa3b, v157
	v_exp_f32_e32 v0, v0
	v_mfma_f32_16x16x32_bf16 v[164:167], v[14:17], v[168:171], v[164:167]
	v_add_f32_e32 v0, 1.0, v0
	v_rcp_f32_e32 v0, v0
	s_nop 0
	v_mul_f32_e32 v0, v23, v0
	v_exp_f32_e32 v0, v0
	s_waitcnt vmcnt(5)
	s_nop 1
	v_fmamk_f32 v35, v164, 0xbfb8aa3b, v155
	v_exp_f32_e32 v35, v35
	v_fma_f32 v36, -v0, v0, 1.0
	v_max_f32_e32 v36, 0, v36
	ds_write_b32 v74, v0
	v_add_f32_e32 v35, 1.0, v35
	v_sqrt_f32_e32 v37, v36
	v_rcp_f32_e32 v35, v35
	v_mov_b32_e32 v0, v37
	v_fmamk_f32 v37, v161, 0xbfb8aa3b, v157
	v_exp_f32_e32 v37, v37
	s_nop 0
	v_add_f32_e32 v36, 1.0, v37
	v_rcp_f32_e32 v36, v36
	v_mul_f32_e32 v0, v35, v0
	s_waitcnt lgkmcnt(0)
	v_mul_f32_e32 v0, v186, v0
	ds_write_b32 v75, v0
	v_mul_f32_e32 v0, v23, v36
	v_exp_f32_e32 v0, v0
	v_fmamk_f32 v35, v165, 0xbfb8aa3b, v155
	v_exp_f32_e32 v35, v35
	v_fma_f32 v36, -v0, v0, 1.0
	v_max_f32_e32 v36, 0, v36
	ds_write_b32 v76, v0
	v_add_f32_e32 v35, 1.0, v35
	v_sqrt_f32_e32 v37, v36
	v_rcp_f32_e32 v35, v35
	v_mov_b32_e32 v0, v37
	v_fmamk_f32 v37, v162, 0xbfb8aa3b, v157
	v_exp_f32_e32 v37, v37
	s_nop 0
	v_add_f32_e32 v36, 1.0, v37
	v_rcp_f32_e32 v36, v36
	v_mul_f32_e32 v0, v35, v0
	v_mul_f32_e32 v0, v187, v0
	ds_write_b32 v77, v0
	v_mul_f32_e32 v0, v23, v36
	v_exp_f32_e32 v0, v0
	v_fmamk_f32 v35, v166, 0xbfb8aa3b, v155
	v_exp_f32_e32 v35, v35
	v_fma_f32 v36, -v0, v0, 1.0
	v_max_f32_e32 v36, 0, v36
	ds_write_b32 v78, v0
	v_add_f32_e32 v35, 1.0, v35
	v_sqrt_f32_e32 v37, v36
	v_rcp_f32_e32 v35, v35
	v_mov_b32_e32 v0, v37
	v_fmamk_f32 v37, v163, 0xbfb8aa3b, v157
	v_exp_f32_e32 v37, v37
	s_nop 0
	v_add_f32_e32 v36, 1.0, v37
	v_rcp_f32_e32 v36, v36
	v_mul_f32_e32 v0, v35, v0
	v_mul_f32_e32 v0, v188, v0
	ds_write_b32 v79, v0
	v_mul_f32_e32 v0, v23, v36
	v_exp_f32_e32 v0, v0
	v_fmamk_f32 v35, v167, 0xbfb8aa3b, v155
	v_exp_f32_e32 v35, v35
	v_fma_f32 v36, -v0, v0, 1.0
	v_max_f32_e32 v36, 0, v36
	ds_write_b32 v80, v0
	v_add_f32_e32 v35, 1.0, v35
	v_sqrt_f32_e32 v37, v36
	v_rcp_f32_e32 v35, v35
	v_mov_b32_e32 v0, v37
	v_mul_f32_e32 v0, v35, v0
	v_mul_f32_e32 v0, v0, v189
	ds_write_b32 v81, v0
	ds_read_b128 v[160:163], v72 offset:36864
	ds_read_b128 v[164:167], v72 offset:36928
	s_waitcnt lgkmcnt(1)
; __device__ __forceinline__ float sigm(float x) { return __builtin_amdgcn_rcpf(1.0f + __expf(-x)); }
; template <int PASS>
; __device__ void lru_items(const Params& p, unsigned char* shm, int l) {
;     ...
;           for (int jt = 0; jt < 4; ++jt) {
;               f32x4 accr = (f32x4){0.f, 0.f, 0.f, 0.f}, acci = (f32x4){0.f, 0.f, 0.f, 0.f};
;               const bf16_t* wr_ = wt + ((d * 2 + 0) * 64 + jt * 16 + fr) * 72 + fq * 8; const bf16_t* wi_ = wt + ((d * 2 + 1) * 64 + jt * 16 + fr) * 72 + fq * 8;
;               accr = __builtin_amdgcn_mfma_f32_16x16x32_bf16(a0, *(const bf16x8*)wr_, accr, 0, 0, 0);
;               accr = __builtin_amdgcn_mfma_f32_16x16x32_bf16(a1, *(const bf16x8*)(wr_ + 32), accr, 0, 0, 0);
;               acci = __builtin_amdgcn_mfma_f32_16x16x32_bf16(a0, *(const bf16x8*)wi_, acci, 0, 0, 0);
;               acci = __builtin_amdgcn_mfma_f32_16x16x32_bf16(a1, *(const bf16x8*)(wi_ + 32), acci, 0, 0, 0);
;               const int j = jt * 16 + fr;
; #pragma unroll
;               for (int i = 0; i < 4; ++i) { const int t = tt * 16 + fq * 4 + i;
;                   const float r = sigm(accr[i] + gba[jt]), ig = sigm(acci[i] + gbx[jt]), a = __expf(r * gsp[jt]);
;                   As[(d * 64 + t) * 64 + j] = a;
;                   Bs[(d * 64 + t) * 64 + j] = sqrtf(fmaxf(1.0f - a * a, 0.f)) * ig * xcf[t * 65 + j]; }
;           } }
	v_mfma_f32_16x16x32_bf16 v[160:163], v[18:21], v[160:163], 0
	ds_read_b128 v[168:171], v73 offset:46144
	s_waitcnt lgkmcnt(1)
	v_mfma_f32_16x16x32_bf16 v[160:163], v[14:17], v[164:167], v[160:163]
	ds_read_b128 v[164:167], v73 offset:46080
	s_waitcnt lgkmcnt(0)
	v_mfma_f32_16x16x32_bf16 v[164:167], v[18:21], v[164:167], 0
	s_nop 4
	v_fmamk_f32 v0, v160, 0xbfb8aa3b, v158
	v_exp_f32_e32 v0, v0
	v_mfma_f32_16x16x32_bf16 v[164:167], v[14:17], v[168:171], v[164:167]
	v_add_f32_e32 v0, 1.0, v0
	v_rcp_f32_e32 v0, v0
	s_nop 0
	v_mul_f32_e32 v0, v22, v0
	v_exp_f32_e32 v0, v0
	s_waitcnt vmcnt(4)
	s_nop 1
	v_fmamk_f32 v35, v164, 0xbfb8aa3b, v156
	v_exp_f32_e32 v35, v35
	v_fma_f32 v36, -v0, v0, 1.0
	v_max_f32_e32 v36, 0, v36
	ds_write_b32 v82, v0
	v_add_f32_e32 v35, 1.0, v35
	v_sqrt_f32_e32 v37, v36
	v_rcp_f32_e32 v35, v35
	v_mov_b32_e32 v0, v37
	v_fmamk_f32 v37, v161, 0xbfb8aa3b, v158
	v_exp_f32_e32 v37, v37
	s_nop 0
	v_add_f32_e32 v36, 1.0, v37
	v_rcp_f32_e32 v36, v36
	v_mul_f32_e32 v0, v35, v0
	v_mul_f32_e32 v0, v190, v0
	ds_write_b32 v83, v0
	v_mul_f32_e32 v0, v22, v36
	v_exp_f32_e32 v0, v0
	v_fmamk_f32 v35, v165, 0xbfb8aa3b, v156
	v_exp_f32_e32 v35, v35
	v_fma_f32 v36, -v0, v0, 1.0
	v_max_f32_e32 v36, 0, v36
	ds_write_b32 v84, v0
	v_add_f32_e32 v35, 1.0, v35
	v_sqrt_f32_e32 v37, v36
	v_rcp_f32_e32 v35, v35
	v_mov_b32_e32 v0, v37
	v_fmamk_f32 v37, v162, 0xbfb8aa3b, v158
	v_exp_f32_e32 v37, v37
	s_nop 0
	v_add_f32_e32 v36, 1.0, v37
	v_rcp_f32_e32 v36, v36
	v_mul_f32_e32 v0, v35, v0
	v_mul_f32_e32 v0, v191, v0
	ds_write_b32 v85, v0
	v_mul_f32_e32 v0, v22, v36
	v_exp_f32_e32 v0, v0
	v_fmamk_f32 v35, v166, 0xbfb8aa3b, v156
	v_exp_f32_e32 v35, v35
	v_fma_f32 v36, -v0, v0, 1.0
	v_max_f32_e32 v36, 0, v36
	ds_write_b32 v86, v0
	v_add_f32_e32 v35, 1.0, v35
	v_sqrt_f32_e32 v37, v36
	v_rcp_f32_e32 v35, v35
	v_mov_b32_e32 v0, v37
	v_fmamk_f32 v37, v163, 0xbfb8aa3b, v158
	v_exp_f32_e32 v37, v37
	s_nop 0
	v_add_f32_e32 v36, 1.0, v37
	v_rcp_f32_e32 v36, v36
	v_mul_f32_e32 v0, v35, v0
	v_mul_f32_e32 v0, v192, v0
	ds_write_b32 v87, v0
	v_mul_f32_e32 v0, v22, v36
	v_exp_f32_e32 v0, v0
	v_fmamk_f32 v35, v167, 0xbfb8aa3b, v156
	v_exp_f32_e32 v35, v35
	v_fma_f32 v36, -v0, v0, 1.0
	v_max_f32_e32 v36, 0, v36
	ds_write_b32 v88, v0
	v_add_f32_e32 v35, 1.0, v35
	v_sqrt_f32_e32 v37, v36
	v_rcp_f32_e32 v35, v35
	v_mov_b32_e32 v0, v37
	v_mul_f32_e32 v0, v35, v0
	v_mul_f32_e32 v0, v0, v193
	ds_write_b32 v89, v0
	ds_read_b128 v[160:163], v72 offset:39168
	ds_read_b128 v[164:167], v72 offset:39232
	s_waitcnt lgkmcnt(1)
	v_mfma_f32_16x16x32_bf16 v[160:163], v[18:21], v[160:163], 0
	ds_read_b128 v[168:171], v73 offset:48448
	s_waitcnt lgkmcnt(1)
	v_mfma_f32_16x16x32_bf16 v[160:163], v[14:17], v[164:167], v[160:163]
	ds_read_b128 v[164:167], v73 offset:48384
	s_waitcnt lgkmcnt(0)
	v_mfma_f32_16x16x32_bf16 v[164:167], v[18:21], v[164:167], 0
	s_nop 4
	v_fmamk_f32 v0, v160, 0xbfb8aa3b, v40
	v_exp_f32_e32 v0, v0
	v_mfma_f32_16x16x32_bf16 v[164:167], v[14:17], v[168:171], v[164:167]
	v_add_f32_e32 v0, 1.0, v0
	v_rcp_f32_e32 v0, v0
	s_nop 0
	v_mul_f32_e32 v0, v25, v0
	v_exp_f32_e32 v0, v0
	s_waitcnt vmcnt(3)
	s_nop 1
	v_fmamk_f32 v35, v164, 0xbfb8aa3b, v38
	v_exp_f32_e32 v35, v35
	v_fma_f32 v36, -v0, v0, 1.0
	v_max_f32_e32 v36, 0, v36
	ds_write_b32 v90, v0
	v_add_f32_e32 v35, 1.0, v35
	v_sqrt_f32_e32 v37, v36
	v_rcp_f32_e32 v35, v35
	v_mov_b32_e32 v0, v37
	v_fmamk_f32 v37, v161, 0xbfb8aa3b, v40
	v_exp_f32_e32 v37, v37
	s_nop 0
	v_add_f32_e32 v36, 1.0, v37
	v_rcp_f32_e32 v36, v36
	v_mul_f32_e32 v0, v35, v0
	v_mul_f32_e32 v0, v194, v0
	ds_write_b32 v91, v0
	v_mul_f32_e32 v0, v25, v36
	v_exp_f32_e32 v0, v0
	v_fmamk_f32 v35, v165, 0xbfb8aa3b, v38
	v_exp_f32_e32 v35, v35
	v_fma_f32 v36, -v0, v0, 1.0
	v_max_f32_e32 v36, 0, v36
	ds_write_b32 v92, v0
	v_add_f32_e32 v35, 1.0, v35
	v_sqrt_f32_e32 v37, v36
	v_rcp_f32_e32 v35, v35
	v_mov_b32_e32 v0, v37
	v_fmamk_f32 v37, v162, 0xbfb8aa3b, v40
	v_exp_f32_e32 v37, v37
	s_nop 0
	v_add_f32_e32 v36, 1.0, v37
	v_rcp_f32_e32 v36, v36
	v_mul_f32_e32 v0, v35, v0
	v_mul_f32_e32 v0, v196, v0
	ds_write_b32 v93, v0
	v_mul_f32_e32 v0, v25, v36
	v_exp_f32_e32 v0, v0
	v_fmamk_f32 v35, v166, 0xbfb8aa3b, v38
	v_exp_f32_e32 v35, v35
	v_fma_f32 v36, -v0, v0, 1.0
	v_max_f32_e32 v36, 0, v36
	ds_write_b32 v94, v0
	v_add_f32_e32 v35, 1.0, v35
	v_sqrt_f32_e32 v37, v36
	v_rcp_f32_e32 v35, v35
	v_mov_b32_e32 v0, v37
	v_fmamk_f32 v37, v163, 0xbfb8aa3b, v40
	v_exp_f32_e32 v37, v37
	s_nop 0
	v_add_f32_e32 v36, 1.0, v37
	v_rcp_f32_e32 v36, v36
	v_mul_f32_e32 v0, v35, v0
	v_mul_f32_e32 v0, v197, v0
	ds_write_b32 v95, v0
	v_mul_f32_e32 v0, v25, v36
	v_exp_f32_e32 v0, v0
	v_fmamk_f32 v35, v167, 0xbfb8aa3b, v38
	v_exp_f32_e32 v35, v35
	v_fma_f32 v36, -v0, v0, 1.0
	v_max_f32_e32 v36, 0, v36
	ds_write_b32 v96, v0
	v_add_f32_e32 v35, 1.0, v35
	v_sqrt_f32_e32 v37, v36
	v_rcp_f32_e32 v35, v35
	v_mov_b32_e32 v0, v37
	v_mul_f32_e32 v0, v35, v0
	v_mul_f32_e32 v0, v0, v198
	ds_write_b32 v97, v0
	ds_read_b128 v[160:163], v72 offset:41472
	ds_read_b128 v[164:167], v72 offset:41536
	s_waitcnt lgkmcnt(1)
; __device__ __forceinline__ float sigm(float x) { return __builtin_amdgcn_rcpf(1.0f + __expf(-x)); }
; template <int PASS>
; __device__ void lru_items(const Params& p, unsigned char* shm, int l) {
;     ...
;           for (int jt = 0; jt < 4; ++jt) {
;               f32x4 accr = (f32x4){0.f, 0.f, 0.f, 0.f}, acci = (f32x4){0.f, 0.f, 0.f, 0.f};
;               const bf16_t* wr_ = wt + ((d * 2 + 0) * 64 + jt * 16 + fr) * 72 + fq * 8; const bf16_t* wi_ = wt + ((d * 2 + 1) * 64 + jt * 16 + fr) * 72 + fq * 8;
;               accr = __builtin_amdgcn_mfma_f32_16x16x32_bf16(a0, *(const bf16x8*)wr_, accr, 0, 0, 0);
;               accr = __builtin_amdgcn_mfma_f32_16x16x32_bf16(a1, *(const bf16x8*)(wr_ + 32), accr, 0, 0, 0);
;               acci = __builtin_amdgcn_mfma_f32_16x16x32_bf16(a0, *(const bf16x8*)wi_, acci, 0, 0, 0);
;               acci = __builtin_amdgcn_mfma_f32_16x16x32_bf16(a1, *(const bf16x8*)(wi_ + 32), acci, 0, 0, 0);
;               const int j = jt * 16 + fr;
; #pragma unroll
;               for (int i = 0; i < 4; ++i) { const int t = tt * 16 + fq * 4 + i;
;                   const float r = sigm(accr[i] + gba[jt]), ig = sigm(acci[i] + gbx[jt]), a = __expf(r * gsp[jt]);
;                   As[(d * 64 + t) * 64 + j] = a;
;                   Bs[(d * 64 + t) * 64 + j] = sqrtf(fmaxf(1.0f - a * a, 0.f)) * ig * xcf[t * 65 + j]; }
;           } }
;         __syncthreads();
;         {
;             const int seg = tid >> 7, d = (tid >> 6) & 1, j = tid & 63;
;             float h = 0.f, P = 1.f;
; #pragma unroll
;             for (int s = 0; s < 16; ++s) { const int st = seg * 16 + s, t = d ? 63 - st : st; const float a = As[(d * 64 + t) * 64 + j]; h = a * h + Bs[(d * 64 + t) * 64 + j]; P *= a; }
;             Pq[seg * 128 + (tid & 127)] = P; Hq[seg * 128 + (tid & 127)] = h;
;             __syncthreads();
;             if (PASS == 0) {
;                 if (tid < 128) { float hh = Hq[tid], PP = Pq[tid];
; #pragma unroll
;                     for (int q = 1; q < 4; ++q) { const float pq = Pq[q * 128 + tid]; hh = pq * hh + Hq[q * 128 + tid]; PP *= pq; }
;                     SA[so] = PP; SH[so] = hh; }
;             } else {
;                 float c = cin;
; #pragma unroll
;                 for (int q = 0; q < 3; ++q) if (q < seg) c = Pq[q * 128 + (tid & 127)] * c + Hq[q * 128 + (tid & 127)];
	v_mfma_f32_16x16x32_bf16 v[160:163], v[18:21], v[160:163], 0
	ds_read_b128 v[168:171], v73 offset:50752
	s_waitcnt lgkmcnt(1)
	v_mfma_f32_16x16x32_bf16 v[160:163], v[14:17], v[164:167], v[160:163]
	ds_read_b128 v[164:167], v73 offset:50688
	s_waitcnt lgkmcnt(0)
	v_mfma_f32_16x16x32_bf16 v[18:21], v[18:21], v[164:167], 0
	s_nop 4
	v_fmamk_f32 v0, v160, 0xbfb8aa3b, v41
	v_exp_f32_e32 v0, v0
	s_nop 0
	v_mfma_f32_16x16x32_bf16 v[14:17], v[14:17], v[168:171], v[18:21]
	v_add_f32_e32 v0, 1.0, v0
	v_rcp_f32_e32 v0, v0
	s_nop 0
	v_mul_f32_e32 v0, v24, v0
	v_exp_f32_e32 v0, v0
	s_waitcnt vmcnt(2)
	s_nop 1
	v_fmamk_f32 v14, v14, 0xbfb8aa3b, v39
	v_exp_f32_e32 v14, v14
	v_fma_f32 v18, -v0, v0, 1.0
	v_max_f32_e32 v18, 0, v18
	ds_write_b32 v98, v0
	v_add_f32_e32 v14, 1.0, v14
	v_sqrt_f32_e32 v19, v18
	v_rcp_f32_e32 v14, v14
	v_mov_b32_e32 v0, v19
	v_fmamk_f32 v19, v161, 0xbfb8aa3b, v41
	v_exp_f32_e32 v19, v19
	s_nop 0
	v_add_f32_e32 v18, 1.0, v19
	v_rcp_f32_e32 v18, v18
	v_mul_f32_e32 v0, v14, v0
	v_mul_f32_e32 v0, v199, v0
	ds_write_b32 v99, v0
	v_mul_f32_e32 v0, v24, v18
	v_exp_f32_e32 v0, v0
	v_fmamk_f32 v14, v15, 0xbfb8aa3b, v39
	v_exp_f32_e32 v14, v14
	v_fma_f32 v15, -v0, v0, 1.0
	v_max_f32_e32 v15, 0, v15
	ds_write_b32 v100, v0
	v_add_f32_e32 v14, 1.0, v14
	v_sqrt_f32_e32 v18, v15
	v_rcp_f32_e32 v14, v14
	v_mov_b32_e32 v0, v18
	v_fmamk_f32 v18, v162, 0xbfb8aa3b, v41
	v_exp_f32_e32 v18, v18
	s_nop 0
	v_add_f32_e32 v15, 1.0, v18
	v_rcp_f32_e32 v15, v15
	v_mul_f32_e32 v0, v14, v0
	v_mul_f32_e32 v0, v200, v0
	ds_write_b32 v101, v0
	v_mul_f32_e32 v0, v24, v15
	v_exp_f32_e32 v0, v0
	v_fmamk_f32 v14, v16, 0xbfb8aa3b, v39
	v_exp_f32_e32 v14, v14
	v_fma_f32 v15, -v0, v0, 1.0
	v_max_f32_e32 v15, 0, v15
	ds_write_b32 v102, v0
	v_add_f32_e32 v14, 1.0, v14
	v_sqrt_f32_e32 v16, v15
	v_rcp_f32_e32 v14, v14
	v_mov_b32_e32 v0, v16
	v_fmamk_f32 v16, v163, 0xbfb8aa3b, v41
	v_exp_f32_e32 v16, v16
	s_nop 0
	v_add_f32_e32 v15, 1.0, v16
	v_rcp_f32_e32 v15, v15
	v_mul_f32_e32 v0, v14, v0
	v_mul_f32_e32 v0, v201, v0
	ds_write_b32 v103, v0
	v_mul_f32_e32 v0, v24, v15
	v_exp_f32_e32 v0, v0
	v_fmamk_f32 v14, v17, 0xbfb8aa3b, v39
	v_exp_f32_e32 v14, v14
	v_fma_f32 v15, -v0, v0, 1.0
	v_max_f32_e32 v15, 0, v15
	ds_write_b32 v104, v0
	v_add_f32_e32 v14, 1.0, v14
	v_sqrt_f32_e32 v16, v15
	v_rcp_f32_e32 v14, v14
	v_mov_b32_e32 v0, v16
	v_mul_f32_e32 v0, v14, v0
	v_mul_f32_e32 v0, v0, v202
	ds_write_b32 v105, v0
	s_waitcnt lgkmcnt(0)
	s_barrier
	ds_read_b32 v183, v51
	ds_read_b32 v184, v106
	ds_read_b32 v185, v107
	ds_read_b32 v186, v108
	ds_read_b32 v187, v109
	ds_read_b32 v188, v110
	ds_read_b32 v189, v111
	ds_read_b32 v190, v112
	ds_read_b32 v191, v113
	ds_read_b32 v192, v114
	ds_read_b32 v193, v115
	ds_read_b32 v194, v116
	ds_read_b32 v196, v117
	ds_read_b32 v197, v118
	ds_read_b32 v198, v119
	ds_read_b32 v199, v120
	ds_read_b32 v200, v121
	ds_read_b32 v201, v122
	ds_read_b32 v202, v123
	ds_read_b32 v203, v124
	ds_read_b32 v204, v125
	ds_read_b32 v205, v126
	ds_read_b32 v206, v127
	ds_read_b32 v207, v128
	ds_read_b32 v208, v129
	ds_read_b32 v209, v130
	ds_read_b32 v210, v131
	ds_read_b32 v211, v132
	ds_read_b32 v212, v133
	ds_read_b32 v213, v134
	ds_read_b32 v214, v135
	ds_read_b32 v215, v136
	s_waitcnt lgkmcnt(0)
	v_fmac_f32_e32 v184, 0, v183
	v_fmac_f32_e32 v186, v184, v185
	v_mul_f32_e32 v183, v183, v185
	v_fmac_f32_e32 v188, v186, v187
	v_mul_f32_e32 v183, v183, v187
	v_fmac_f32_e32 v190, v188, v189
	v_mul_f32_e32 v183, v183, v189
	v_fmac_f32_e32 v192, v190, v191
	v_mul_f32_e32 v183, v183, v191
	v_fmac_f32_e32 v194, v192, v193
	v_mul_f32_e32 v183, v183, v193
	v_fmac_f32_e32 v197, v194, v196
	v_mul_f32_e32 v183, v183, v196
	v_fmac_f32_e32 v199, v197, v198
	v_mul_f32_e32 v183, v183, v198
	v_fmac_f32_e32 v201, v199, v200
	v_mul_f32_e32 v183, v183, v200
	v_fmac_f32_e32 v203, v201, v202
	v_mul_f32_e32 v183, v183, v202
	v_fmac_f32_e32 v205, v203, v204
	v_mul_f32_e32 v183, v183, v204
	v_fmac_f32_e32 v207, v205, v206
	v_mul_f32_e32 v183, v183, v206
	v_mul_f32_e32 v183, v183, v208
	v_fmac_f32_e32 v209, v207, v208
	v_mul_f32_e32 v183, v183, v210
	v_fmac_f32_e32 v211, v209, v210
	v_mul_f32_e32 v183, v183, v212
	v_fmac_f32_e32 v213, v211, v212
	v_mul_f32_e32 v183, v183, v214
	v_fmac_f32_e32 v215, v213, v214
	ds_write_b32 v48, v183
	ds_write_b32 v49, v215
	s_waitcnt lgkmcnt(0)
	s_barrier
	ds_read_b32 v183, v138
	ds_read_b32 v184, v137
	ds_read_b32 v185, v140
	ds_read_b32 v186, v139
	ds_read_b32 v187, v142
	ds_read_b32 v188, v141
	s_waitcnt vmcnt(0) lgkmcnt(0)
	v_fmac_f32_e32 v184, v34, v183
	v_cndmask_b32_e64 v34, v34, v184, s[38:39]
	v_fmac_f32_e32 v186, v34, v185
	v_cndmask_b32_e64 v34, v34, v186, s[40:41]
	v_fmac_f32_e32 v188, v34, v187
	v_cndmask_b32_e64 v34, v34, v188, s[42:43]
	s_branch .LBB0_199

; __device__ __forceinline__ bf16_t f2bf(float f) { return (bf16_t)(cvt_pk_bf16(f, 0.f) & 0xffffu); }
; __device__ __forceinline__ float bf2f(bf16_t b) { return __uint_as_float(((unsigned)b) << 16); }
; __device__ __forceinline__ float sigm(float x) { return __builtin_amdgcn_rcpf(1.0f + __expf(-x)); }
; template <int PASS>
; __device__ void lru_items(const Params& p, unsigned char* shm, int l) {
;     ...
;         { const int j = tid & 63;
; #pragma unroll
;           for (int i = 0; i < 8; ++i) { const int t = (tid >> 6) + 8 * i;
;               const float v = cb + bf2f(xraw[t * 64 + j]) * c0 + bf2f(xraw[(t + 1) * 64 + j]) * c1 + bf2f(xraw[(t + 2) * 64 + j]) * c2 + bf2f(xraw[(t + 3) * 64 + j]) * c3;
;               xcf[t * 65 + j] = v; xcb[t * 72 + j] = f2bf(v); } }
;         __syncthreads();
;         { const int d = w >> 2, tt = w & 3;
;           const bf16x8 a0 = *(const bf16x8*)(xcb + (tt * 16 + fr) * 72 + fq * 8), a1 = *(const bf16x8*)(xcb + (tt * 16 + fr) * 72 + 32 + fq * 8);
; #pragma unroll
;           for (int jt = 0; jt < 4; ++jt) {
;               f32x4 accr = (f32x4){0.f, 0.f, 0.f, 0.f}, acci = (f32x4){0.f, 0.f, 0.f, 0.f};
;               const bf16_t* wr_ = wt + ((d * 2 + 0) * 64 + jt * 16 + fr) * 72 + fq * 8; const bf16_t* wi_ = wt + ((d * 2 + 1) * 64 + jt * 16 + fr) * 72 + fq * 8;
;               accr = __builtin_amdgcn_mfma_f32_16x16x32_bf16(a0, *(const bf16x8*)wr_, accr, 0, 0, 0);
;               accr = __builtin_amdgcn_mfma_f32_16x16x32_bf16(a1, *(const bf16x8*)(wr_ + 32), accr, 0, 0, 0);
;               acci = __builtin_amdgcn_mfma_f32_16x16x32_bf16(a0, *(const bf16x8*)wi_, acci, 0, 0, 0);
;               acci = __builtin_amdgcn_mfma_f32_16x16x32_bf16(a1, *(const bf16x8*)(wi_ + 32), acci, 0, 0, 0);
;               const int j = jt * 16 + fr;
; #pragma unroll
;               for (int i = 0; i < 4; ++i) { const int t = tt * 16 + fq * 4 + i;
;                   const float r = sigm(accr[i] + gba[jt]), ig = sigm(acci[i] + gbx[jt]), a = __expf(r * gsp[jt]);
;                   As[(d * 64 + t) * 64 + j] = a;
;                   Bs[(d * 64 + t) * 64 + j] = sqrtf(fmaxf(1.0f - a * a, 0.f)) * ig * xcf[t * 65 + j]; }
;           } }
.LBB0_310:
	s_mov_b32 s0, 0xf800000
	v_lshrrev_b32_e32 v183, 6, v229
	v_and_b32_e32 v184, 63, v229
	v_lshlrev_b32_e32 v185, 10, v183
	v_lshl_add_u32 v185, v184, 1, v185
	ds_read_u16 v186, v185
	ds_read_u16 v187, v185 offset:128
	ds_read_u16 v188, v185 offset:256
	ds_read_u16 v189, v185 offset:384
	ds_read_u16 v190, v185 offset:512
	ds_read_u16 v191, v185 offset:640
	ds_read_u16 v192, v185 offset:768
	ds_read_u16 v193, v185 offset:896
	ds_read_u16 v194, v185 offset:1024
	ds_read_u16 v196, v185 offset:1152
	ds_read_u16 v197, v185 offset:1280
	v_mul_u32_u24_e32 v206, 0x820, v183
	v_lshl_add_u32 v206, v184, 2, v206
	v_mul_u32_u24_e32 v207, 0x480, v183
	v_lshl_add_u32 v207, v184, 1, v207
	s_waitcnt lgkmcnt(0)
	v_lshlrev_b32_e32 v186, 16, v186
	v_lshlrev_b32_e32 v187, 16, v187
	v_lshlrev_b32_e32 v188, 16, v188
	v_lshlrev_b32_e32 v189, 16, v189
	v_lshlrev_b32_e32 v190, 16, v190
	v_lshlrev_b32_e32 v191, 16, v191
	v_lshlrev_b32_e32 v192, 16, v192
	v_lshlrev_b32_e32 v193, 16, v193
	v_lshlrev_b32_e32 v194, 16, v194
	v_lshlrev_b32_e32 v196, 16, v196
	v_lshlrev_b32_e32 v197, 16, v197
	v_fma_f32 v198, v149, v186, v148
	v_fma_f32 v199, v149, v187, v148
	v_fma_f32 v200, v149, v188, v148
	v_fma_f32 v201, v149, v189, v148
	v_fma_f32 v202, v149, v190, v148
	v_fma_f32 v203, v149, v191, v148
	v_fma_f32 v204, v149, v192, v148
	v_fma_f32 v205, v149, v193, v148
	v_fmac_f32_e32 v198, v152, v187
	v_fmac_f32_e32 v199, v152, v188
	v_fmac_f32_e32 v200, v152, v189
	v_fmac_f32_e32 v201, v152, v190
	v_fmac_f32_e32 v202, v152, v191
	v_fmac_f32_e32 v203, v152, v192
	v_fmac_f32_e32 v204, v152, v193
	v_fmac_f32_e32 v205, v152, v194
	v_fmac_f32_e32 v198, v151, v188
	v_fmac_f32_e32 v199, v151, v189
	v_fmac_f32_e32 v200, v151, v190
	v_fmac_f32_e32 v201, v151, v191
	v_fmac_f32_e32 v202, v151, v192
	v_fmac_f32_e32 v203, v151, v193
	v_fmac_f32_e32 v204, v151, v194
	v_fmac_f32_e32 v205, v151, v196
	v_fmac_f32_e32 v198, v150, v189
	v_fmac_f32_e32 v199, v150, v190
	v_fmac_f32_e32 v200, v150, v191
	v_fmac_f32_e32 v201, v150, v192
	v_fmac_f32_e32 v202, v150, v193
	v_fmac_f32_e32 v203, v150, v194
	v_fmac_f32_e32 v204, v150, v196
	v_fmac_f32_e32 v205, v150, v197
	ds_write_b32 v206, v198 offset:8704
	ds_write_b32 v206, v199 offset:8964
	ds_write_b32 v206, v200 offset:9224
	ds_write_b32 v206, v201 offset:9484
	ds_write_b32 v206, v202 offset:9744
	ds_write_b32 v206, v203 offset:10004
	ds_write_b32 v206, v204 offset:10264
	ds_write_b32 v206, v205 offset:10524
	v_cvt_pk_bf16_f32 v186, v198, v1
	v_cvt_pk_bf16_f32 v187, v199, v1
	ds_write_b16 v207, v186 offset:25344
	v_cvt_pk_bf16_f32 v188, v200, v1
	ds_write_b16 v207, v187 offset:25488
	v_cvt_pk_bf16_f32 v189, v201, v1
	ds_write_b16 v207, v188 offset:25632
	v_cvt_pk_bf16_f32 v190, v202, v1
	ds_write_b16 v207, v189 offset:25776
	v_cvt_pk_bf16_f32 v191, v203, v1
	ds_write_b16 v207, v190 offset:25920
	v_cvt_pk_bf16_f32 v192, v204, v1
	ds_write_b16 v207, v191 offset:26064
	v_cvt_pk_bf16_f32 v193, v205, v1
	ds_write_b16 v207, v192 offset:26208
	ds_write_b16 v207, v193 offset:26352
	s_waitcnt lgkmcnt(0)
	s_barrier
	ds_read_b32 v186, v147 offset:8704
	ds_read_b32 v187, v147 offset:8964
	ds_read_b32 v188, v147 offset:9224
	ds_read_b32 v189, v147 offset:9484
	ds_read_b32 v190, v147 offset:8768
	ds_read_b32 v191, v147 offset:9028
	ds_read_b32 v192, v147 offset:9288
	ds_read_b32 v193, v147 offset:9548
	ds_read_b32 v194, v147 offset:8832
	ds_read_b32 v196, v147 offset:9092
	ds_read_b32 v197, v147 offset:9352
	ds_read_b32 v198, v147 offset:9612
	ds_read_b32 v199, v147 offset:8896
	ds_read_b32 v200, v147 offset:9156
	ds_read_b32 v201, v147 offset:9416
	ds_read_b32 v202, v147 offset:9676
	ds_read_b128 v[14:17], v44 offset:25344
	ds_read_b128 v[10:13], v44 offset:25408
	ds_read_b128 v[32:35], v67 offset:34560
	ds_read_b128 v[154:157], v67 offset:34624
	s_waitcnt lgkmcnt(1)
	v_mfma_f32_16x16x32_bf16 v[32:35], v[14:17], v[32:35], 0
	ds_read_b128 v[158:161], v68 offset:43840
	s_waitcnt lgkmcnt(1)
	v_mfma_f32_16x16x32_bf16 v[32:35], v[10:13], v[154:157], v[32:35]
	ds_read_b128 v[154:157], v68 offset:43776
	s_waitcnt lgkmcnt(0)
	v_mfma_f32_16x16x32_bf16 v[154:157], v[14:17], v[154:157], 0
	s_waitcnt vmcnt(7)
	s_nop 3
	v_fmamk_f32 v0, v32, 0xbfb8aa3b, v22
	v_exp_f32_e32 v0, v0
	v_mfma_f32_16x16x32_bf16 v[154:157], v[10:13], v[158:161], v[154:157]
	v_fmamk_f32 v33, v33, 0xbfb8aa3b, v22
	v_add_f32_e32 v0, 1.0, v0
	v_rcp_f32_e32 v0, v0
	v_exp_f32_e32 v33, v33
	s_waitcnt vmcnt(3)
	s_nop 2
	v_fmamk_f32 v32, v154, 0xbfb8aa3b, v38
	v_mul_f32_e32 v0, v19, v0
	v_exp_f32_e32 v0, v0
	v_exp_f32_e32 v32, v32
	v_add_f32_e32 v33, 1.0, v33
	v_rcp_f32_e32 v33, v33
	v_fma_f32 v37, -v0, v0, 1.0
	v_max_f32_e32 v37, 0, v37
	ds_write_b32 v69, v0
	v_add_f32_e32 v32, 1.0, v32
	v_sqrt_f32_e32 v41, v37
	v_rcp_f32_e32 v32, v32
	v_fmamk_f32 v34, v34, 0xbfb8aa3b, v22
	v_mov_b32_e32 v0, v41
	v_exp_f32_e32 v34, v34
	v_mul_f32_e32 v0, v32, v0
	s_waitcnt lgkmcnt(0)
	v_mul_f32_e32 v0, v186, v0
	ds_write_b32 v70, v0
	v_mul_f32_e32 v0, v19, v33
	v_exp_f32_e32 v0, v0
	v_fmamk_f32 v32, v155, 0xbfb8aa3b, v38
	v_exp_f32_e32 v32, v32
	v_fma_f32 v33, -v0, v0, 1.0
	v_max_f32_e32 v33, 0, v33
	ds_write_b32 v71, v0
	v_add_f32_e32 v32, 1.0, v32
	v_sqrt_f32_e32 v37, v33
	v_rcp_f32_e32 v32, v32
	v_mov_b32_e32 v0, v37
	v_add_f32_e32 v33, 1.0, v34
	v_rcp_f32_e32 v33, v33
	v_mul_f32_e32 v0, v32, v0
	v_mul_f32_e32 v0, v187, v0
	ds_write_b32 v72, v0
	v_mul_f32_e32 v0, v19, v33
	v_exp_f32_e32 v0, v0
	v_fmamk_f32 v32, v156, 0xbfb8aa3b, v38
	v_exp_f32_e32 v32, v32
	v_fma_f32 v33, -v0, v0, 1.0
	v_max_f32_e32 v33, 0, v33
	ds_write_b32 v73, v0
	v_add_f32_e32 v32, 1.0, v32
	v_sqrt_f32_e32 v34, v33
	v_rcp_f32_e32 v32, v32
	v_mov_b32_e32 v0, v34
	v_fmamk_f32 v34, v35, 0xbfb8aa3b, v22
	v_exp_f32_e32 v34, v34
	s_nop 0
	v_add_f32_e32 v33, 1.0, v34
	v_rcp_f32_e32 v33, v33
	v_mul_f32_e32 v0, v32, v0
	v_mul_f32_e32 v0, v188, v0
	ds_write_b32 v74, v0
	v_mul_f32_e32 v0, v19, v33
	v_exp_f32_e32 v0, v0
	v_fmamk_f32 v32, v157, 0xbfb8aa3b, v38
	v_exp_f32_e32 v32, v32
	v_fma_f32 v33, -v0, v0, 1.0
	v_max_f32_e32 v33, 0, v33
	ds_write_b32 v75, v0
	v_add_f32_e32 v32, 1.0, v32
	v_sqrt_f32_e32 v34, v33
	v_rcp_f32_e32 v32, v32
	v_mov_b32_e32 v0, v34
	v_mul_f32_e32 v0, v32, v0
	v_mul_f32_e32 v0, v0, v189
	ds_write_b32 v76, v0
	ds_read_b128 v[32:35], v67 offset:36864
	ds_read_b128 v[154:157], v67 offset:36928
	s_waitcnt lgkmcnt(1)
; __device__ __forceinline__ float sigm(float x) { return __builtin_amdgcn_rcpf(1.0f + __expf(-x)); }
; template <int PASS>
; __device__ void lru_items(const Params& p, unsigned char* shm, int l) {
;     ...
;           for (int jt = 0; jt < 4; ++jt) {
;               f32x4 accr = (f32x4){0.f, 0.f, 0.f, 0.f}, acci = (f32x4){0.f, 0.f, 0.f, 0.f};
;               const bf16_t* wr_ = wt + ((d * 2 + 0) * 64 + jt * 16 + fr) * 72 + fq * 8; const bf16_t* wi_ = wt + ((d * 2 + 1) * 64 + jt * 16 + fr) * 72 + fq * 8;
;               accr = __builtin_amdgcn_mfma_f32_16x16x32_bf16(a0, *(const bf16x8*)wr_, accr, 0, 0, 0);
;               accr = __builtin_amdgcn_mfma_f32_16x16x32_bf16(a1, *(const bf16x8*)(wr_ + 32), accr, 0, 0, 0);
;               acci = __builtin_amdgcn_mfma_f32_16x16x32_bf16(a0, *(const bf16x8*)wi_, acci, 0, 0, 0);
;               acci = __builtin_amdgcn_mfma_f32_16x16x32_bf16(a1, *(const bf16x8*)(wi_ + 32), acci, 0, 0, 0);
;               const int j = jt * 16 + fr;
; #pragma unroll
;               for (int i = 0; i < 4; ++i) { const int t = tt * 16 + fq * 4 + i;
;                   const float r = sigm(accr[i] + gba[jt]), ig = sigm(acci[i] + gbx[jt]), a = __expf(r * gsp[jt]);
;                   As[(d * 64 + t) * 64 + j] = a;
;                   Bs[(d * 64 + t) * 64 + j] = sqrtf(fmaxf(1.0f - a * a, 0.f)) * ig * xcf[t * 65 + j]; }
;           } }
	v_mfma_f32_16x16x32_bf16 v[32:35], v[14:17], v[32:35], 0
	ds_read_b128 v[158:161], v68 offset:46144
	s_waitcnt lgkmcnt(1)
	v_mfma_f32_16x16x32_bf16 v[32:35], v[10:13], v[154:157], v[32:35]
	ds_read_b128 v[154:157], v68 offset:46080
	s_waitcnt lgkmcnt(0)
	v_mfma_f32_16x16x32_bf16 v[154:157], v[14:17], v[154:157], 0
	s_nop 4
	v_fmamk_f32 v0, v32, 0xbfb8aa3b, v23
	v_exp_f32_e32 v0, v0
	v_mfma_f32_16x16x32_bf16 v[154:157], v[10:13], v[158:161], v[154:157]
	v_fmamk_f32 v33, v33, 0xbfb8aa3b, v23
	v_add_f32_e32 v0, 1.0, v0
	v_rcp_f32_e32 v0, v0
	v_exp_f32_e32 v33, v33
	s_waitcnt vmcnt(2)
	s_nop 2
	v_fmamk_f32 v32, v154, 0xbfb8aa3b, v39
	v_mul_f32_e32 v0, v18, v0
	v_exp_f32_e32 v0, v0
	v_exp_f32_e32 v32, v32
	v_add_f32_e32 v33, 1.0, v33
	v_rcp_f32_e32 v33, v33
	v_fma_f32 v37, -v0, v0, 1.0
	v_max_f32_e32 v37, 0, v37
	ds_write_b32 v77, v0
	v_add_f32_e32 v32, 1.0, v32
	v_sqrt_f32_e32 v41, v37
	v_rcp_f32_e32 v32, v32
	v_fmamk_f32 v34, v34, 0xbfb8aa3b, v23
	v_mov_b32_e32 v0, v41
	v_exp_f32_e32 v34, v34
	v_mul_f32_e32 v0, v32, v0
	v_mul_f32_e32 v0, v190, v0
	ds_write_b32 v78, v0
	v_mul_f32_e32 v0, v18, v33
	v_exp_f32_e32 v0, v0
	v_fmamk_f32 v32, v155, 0xbfb8aa3b, v39
	v_exp_f32_e32 v32, v32
	v_fma_f32 v33, -v0, v0, 1.0
	v_max_f32_e32 v33, 0, v33
	ds_write_b32 v79, v0
	v_add_f32_e32 v32, 1.0, v32
	v_sqrt_f32_e32 v37, v33
	v_rcp_f32_e32 v32, v32
	v_mov_b32_e32 v0, v37
	v_add_f32_e32 v33, 1.0, v34
	v_rcp_f32_e32 v33, v33
	v_mul_f32_e32 v0, v32, v0
	v_mul_f32_e32 v0, v191, v0
	ds_write_b32 v80, v0
	v_mul_f32_e32 v0, v18, v33
	v_exp_f32_e32 v0, v0
	v_fmamk_f32 v32, v156, 0xbfb8aa3b, v39
	v_exp_f32_e32 v32, v32
	v_fma_f32 v33, -v0, v0, 1.0
	v_max_f32_e32 v33, 0, v33
	ds_write_b32 v81, v0
	v_add_f32_e32 v32, 1.0, v32
	v_sqrt_f32_e32 v34, v33
	v_rcp_f32_e32 v32, v32
	v_mov_b32_e32 v0, v34
	v_fmamk_f32 v34, v35, 0xbfb8aa3b, v23
	v_exp_f32_e32 v34, v34
	s_nop 0
	v_add_f32_e32 v33, 1.0, v34
	v_rcp_f32_e32 v33, v33
	v_mul_f32_e32 v0, v32, v0
	v_mul_f32_e32 v0, v192, v0
	ds_write_b32 v82, v0
	v_mul_f32_e32 v0, v18, v33
	v_exp_f32_e32 v0, v0
	v_fmamk_f32 v32, v157, 0xbfb8aa3b, v39
	v_exp_f32_e32 v32, v32
	v_fma_f32 v33, -v0, v0, 1.0
	v_max_f32_e32 v33, 0, v33
	ds_write_b32 v83, v0
	v_add_f32_e32 v32, 1.0, v32
	v_sqrt_f32_e32 v34, v33
	v_rcp_f32_e32 v32, v32
	v_mov_b32_e32 v0, v34
	v_mul_f32_e32 v0, v32, v0
	v_mul_f32_e32 v0, v0, v193
	ds_write_b32 v84, v0
	ds_read_b128 v[32:35], v67 offset:39168
	ds_read_b128 v[154:157], v67 offset:39232
	s_waitcnt lgkmcnt(1)
	v_mfma_f32_16x16x32_bf16 v[32:35], v[14:17], v[32:35], 0
	ds_read_b128 v[158:161], v68 offset:48448
	s_waitcnt lgkmcnt(1)
	v_mfma_f32_16x16x32_bf16 v[32:35], v[10:13], v[154:157], v[32:35]
	ds_read_b128 v[154:157], v68 offset:48384
	s_waitcnt lgkmcnt(0)
	v_mfma_f32_16x16x32_bf16 v[154:157], v[14:17], v[154:157], 0
	s_nop 4
	v_fmamk_f32 v0, v32, 0xbfb8aa3b, v24
	v_exp_f32_e32 v0, v0
	v_mfma_f32_16x16x32_bf16 v[154:157], v[10:13], v[158:161], v[154:157]
	v_fmamk_f32 v33, v33, 0xbfb8aa3b, v24
	v_add_f32_e32 v0, 1.0, v0
	v_rcp_f32_e32 v0, v0
	v_exp_f32_e32 v33, v33
	s_waitcnt vmcnt(1)
	s_nop 2
	v_fmamk_f32 v32, v154, 0xbfb8aa3b, v40
	v_mul_f32_e32 v0, v21, v0
	v_exp_f32_e32 v0, v0
	v_exp_f32_e32 v32, v32
	v_add_f32_e32 v33, 1.0, v33
	v_rcp_f32_e32 v33, v33
	v_fma_f32 v37, -v0, v0, 1.0
	v_max_f32_e32 v37, 0, v37
	ds_write_b32 v85, v0
	v_add_f32_e32 v32, 1.0, v32
	v_sqrt_f32_e32 v41, v37
	v_rcp_f32_e32 v32, v32
	v_fmamk_f32 v34, v34, 0xbfb8aa3b, v24
	v_mov_b32_e32 v0, v41
	v_exp_f32_e32 v34, v34
	v_mul_f32_e32 v0, v32, v0
	v_mul_f32_e32 v0, v194, v0
	ds_write_b32 v86, v0
	v_mul_f32_e32 v0, v21, v33
	v_exp_f32_e32 v0, v0
	v_fmamk_f32 v32, v155, 0xbfb8aa3b, v40
	v_exp_f32_e32 v32, v32
	v_fma_f32 v33, -v0, v0, 1.0
	v_max_f32_e32 v33, 0, v33
	ds_write_b32 v87, v0
	v_add_f32_e32 v32, 1.0, v32
	v_sqrt_f32_e32 v37, v33
	v_rcp_f32_e32 v32, v32
	v_mov_b32_e32 v0, v37
	v_add_f32_e32 v33, 1.0, v34
	v_rcp_f32_e32 v33, v33
	v_mul_f32_e32 v0, v32, v0
	v_mul_f32_e32 v0, v196, v0
	ds_write_b32 v88, v0
	v_mul_f32_e32 v0, v21, v33
	v_exp_f32_e32 v0, v0
	v_fmamk_f32 v32, v156, 0xbfb8aa3b, v40
	v_exp_f32_e32 v32, v32
	v_fma_f32 v33, -v0, v0, 1.0
	v_max_f32_e32 v33, 0, v33
	ds_write_b32 v89, v0
	v_add_f32_e32 v32, 1.0, v32
	v_sqrt_f32_e32 v34, v33
	v_rcp_f32_e32 v32, v32
	v_mov_b32_e32 v0, v34
	v_fmamk_f32 v34, v35, 0xbfb8aa3b, v24
	v_exp_f32_e32 v34, v34
	s_nop 0
	v_add_f32_e32 v33, 1.0, v34
	v_rcp_f32_e32 v33, v33
	v_mul_f32_e32 v0, v32, v0
	v_mul_f32_e32 v0, v197, v0
	ds_write_b32 v90, v0
	v_mul_f32_e32 v0, v21, v33
	v_exp_f32_e32 v0, v0
	v_fmamk_f32 v32, v157, 0xbfb8aa3b, v40
	v_exp_f32_e32 v32, v32
	v_fma_f32 v33, -v0, v0, 1.0
	v_max_f32_e32 v33, 0, v33
	ds_write_b32 v91, v0
	v_add_f32_e32 v32, 1.0, v32
	v_sqrt_f32_e32 v34, v33
	v_rcp_f32_e32 v32, v32
	v_mov_b32_e32 v0, v34
	v_mul_f32_e32 v0, v32, v0
	v_mul_f32_e32 v0, v0, v198
	ds_write_b32 v92, v0
	ds_read_b128 v[32:35], v67 offset:41472
	ds_read_b128 v[154:157], v67 offset:41536
	s_waitcnt lgkmcnt(1)
	v_mfma_f32_16x16x32_bf16 v[32:35], v[14:17], v[32:35], 0
	ds_read_b128 v[158:161], v68 offset:50752
	s_waitcnt lgkmcnt(1)
; __device__ __forceinline__ float sigm(float x) { return __builtin_amdgcn_rcpf(1.0f + __expf(-x)); }
; template <int PASS>
; __device__ void lru_items(const Params& p, unsigned char* shm, int l) {
;     ...
;               for (int i = 0; i < 4; ++i) { const int t = tt * 16 + fq * 4 + i;
;                   const float r = sigm(accr[i] + gba[jt]), ig = sigm(acci[i] + gbx[jt]), a = __expf(r * gsp[jt]);
;                   As[(d * 64 + t) * 64 + j] = a;
;                   Bs[(d * 64 + t) * 64 + j] = sqrtf(fmaxf(1.0f - a * a, 0.f)) * ig * xcf[t * 65 + j]; }
;           } }
;         __syncthreads();
;         {
;             const int seg = tid >> 7, d = (tid >> 6) & 1, j = tid & 63;
;             float h = 0.f, P = 1.f;
; #pragma unroll
;             for (int s = 0; s < 16; ++s) { const int st = seg * 16 + s, t = d ? 63 - st : st; const float a = As[(d * 64 + t) * 64 + j]; h = a * h + Bs[(d * 64 + t) * 64 + j]; P *= a; }
;             Pq[seg * 128 + (tid & 127)] = P; Hq[seg * 128 + (tid & 127)] = h;
;             __syncthreads();
;             if (PASS == 0) {
;                 if (tid < 128) { float hh = Hq[tid], PP = Pq[tid];
; #pragma unroll
;                     for (int q = 1; q < 4; ++q) { const float pq = Pq[q * 128 + tid]; hh = pq * hh + Hq[q * 128 + tid]; PP *= pq; }
;                     SA[so] = PP; SH[so] = hh; }
	v_mfma_f32_16x16x32_bf16 v[32:35], v[10:13], v[154:157], v[32:35]
	ds_read_b128 v[154:157], v68 offset:50688
	s_waitcnt lgkmcnt(0)
	v_mfma_f32_16x16x32_bf16 v[14:17], v[14:17], v[154:157], 0
	s_nop 4
	v_fmamk_f32 v0, v32, 0xbfb8aa3b, v25
	v_exp_f32_e32 v0, v0
	s_nop 0
	v_mfma_f32_16x16x32_bf16 v[10:13], v[10:13], v[158:161], v[14:17]
	v_add_f32_e32 v0, 1.0, v0
	v_rcp_f32_e32 v0, v0
	s_nop 0
	v_mul_f32_e32 v0, v20, v0
	v_exp_f32_e32 v0, v0
	s_waitcnt vmcnt(0)
	s_nop 1
	v_fmamk_f32 v10, v10, 0xbfb8aa3b, v36
	v_exp_f32_e32 v10, v10
	v_fma_f32 v14, -v0, v0, 1.0
	v_max_f32_e32 v14, 0, v14
	ds_write_b32 v93, v0
	v_add_f32_e32 v10, 1.0, v10
	v_sqrt_f32_e32 v15, v14
	v_rcp_f32_e32 v10, v10
	v_mov_b32_e32 v0, v15
	v_fmamk_f32 v15, v33, 0xbfb8aa3b, v25
	v_exp_f32_e32 v15, v15
	s_nop 0
	v_add_f32_e32 v14, 1.0, v15
	v_rcp_f32_e32 v14, v14
	v_mul_f32_e32 v0, v10, v0
	v_mul_f32_e32 v0, v199, v0
	ds_write_b32 v94, v0
	v_mul_f32_e32 v0, v20, v14
	v_exp_f32_e32 v0, v0
	v_fmamk_f32 v10, v11, 0xbfb8aa3b, v36
	v_exp_f32_e32 v10, v10
	v_fma_f32 v11, -v0, v0, 1.0
	v_max_f32_e32 v11, 0, v11
	ds_write_b32 v95, v0
	v_add_f32_e32 v10, 1.0, v10
	v_sqrt_f32_e32 v14, v11
	v_rcp_f32_e32 v10, v10
	v_mov_b32_e32 v0, v14
	v_fmamk_f32 v14, v34, 0xbfb8aa3b, v25
	v_exp_f32_e32 v14, v14
	s_nop 0
	v_add_f32_e32 v11, 1.0, v14
	v_rcp_f32_e32 v11, v11
	v_mul_f32_e32 v0, v10, v0
	v_mul_f32_e32 v0, v200, v0
	ds_write_b32 v96, v0
	v_mul_f32_e32 v0, v20, v11
	v_exp_f32_e32 v0, v0
	v_fmamk_f32 v10, v12, 0xbfb8aa3b, v36
	v_exp_f32_e32 v10, v10
	v_fma_f32 v11, -v0, v0, 1.0
	v_max_f32_e32 v11, 0, v11
	ds_write_b32 v97, v0
	v_add_f32_e32 v10, 1.0, v10
	v_sqrt_f32_e32 v12, v11
	v_rcp_f32_e32 v10, v10
	v_mov_b32_e32 v0, v12
	v_fmamk_f32 v12, v35, 0xbfb8aa3b, v25
	v_exp_f32_e32 v12, v12
	s_nop 0
	v_add_f32_e32 v11, 1.0, v12
	v_rcp_f32_e32 v11, v11
	v_mul_f32_e32 v0, v10, v0
	v_mul_f32_e32 v0, v201, v0
	ds_write_b32 v98, v0
	v_mul_f32_e32 v0, v20, v11
	v_exp_f32_e32 v0, v0
	v_fmamk_f32 v10, v13, 0xbfb8aa3b, v36
	v_exp_f32_e32 v10, v10
	v_fma_f32 v11, -v0, v0, 1.0
	v_max_f32_e32 v11, 0, v11
	ds_write_b32 v99, v0
	v_add_f32_e32 v10, 1.0, v10
	v_sqrt_f32_e32 v12, v11
	v_rcp_f32_e32 v10, v10
	v_mov_b32_e32 v0, v12
	v_mul_f32_e32 v0, v10, v0
	v_mul_f32_e32 v0, v0, v202
	ds_write_b32 v100, v0
	s_waitcnt lgkmcnt(0)
	s_barrier
	ds_read_b32 v183, v101
	ds_read_b32 v184, v102
	ds_read_b32 v185, v103
	ds_read_b32 v186, v104
	ds_read_b32 v187, v105
	ds_read_b32 v188, v106
	ds_read_b32 v189, v107
	ds_read_b32 v190, v108
	ds_read_b32 v191, v109
	ds_read_b32 v192, v110
	ds_read_b32 v193, v111
	ds_read_b32 v194, v112
	ds_read_b32 v196, v113
	ds_read_b32 v197, v114
	ds_read_b32 v198, v115
	ds_read_b32 v199, v116
	ds_read_b32 v200, v117
	ds_read_b32 v201, v118
	ds_read_b32 v202, v119
	ds_read_b32 v203, v120
	ds_read_b32 v204, v121
	ds_read_b32 v205, v122
	ds_read_b32 v206, v123
	ds_read_b32 v207, v124
	ds_read_b32 v208, v125
	ds_read_b32 v209, v126
	ds_read_b32 v210, v127
	ds_read_b32 v211, v128
	ds_read_b32 v212, v129
	ds_read_b32 v213, v131
	ds_read_b32 v214, v132
	ds_read_b32 v215, v133
	s_waitcnt lgkmcnt(0)
	v_fmac_f32_e32 v184, 0, v183
	v_fmac_f32_e32 v186, v184, v185
	v_mul_f32_e32 v183, v183, v185
	v_fmac_f32_e32 v188, v186, v187
	v_mul_f32_e32 v183, v183, v187
	v_fmac_f32_e32 v190, v188, v189
	v_mul_f32_e32 v183, v183, v189
	v_fmac_f32_e32 v192, v190, v191
	v_mul_f32_e32 v183, v183, v191
	v_fmac_f32_e32 v194, v192, v193
	v_mul_f32_e32 v183, v183, v193
	v_fmac_f32_e32 v197, v194, v196
	v_mul_f32_e32 v183, v183, v196
	v_fmac_f32_e32 v199, v197, v198
	v_mul_f32_e32 v183, v183, v198
	v_fmac_f32_e32 v201, v199, v200
	v_mul_f32_e32 v183, v183, v200
	v_fmac_f32_e32 v203, v201, v202
	v_mul_f32_e32 v183, v183, v202
	v_fmac_f32_e32 v205, v203, v204
	v_mul_f32_e32 v183, v183, v204
	v_fmac_f32_e32 v207, v205, v206
	v_mul_f32_e32 v183, v183, v206
	v_mul_f32_e32 v183, v183, v208
	v_fmac_f32_e32 v209, v207, v208
	v_mul_f32_e32 v183, v183, v210
	v_fmac_f32_e32 v211, v209, v210
	v_mul_f32_e32 v183, v183, v212
	v_fmac_f32_e32 v213, v211, v212
	v_mul_f32_e32 v183, v183, v214
	v_fmac_f32_e32 v215, v213, v214
	ds_write_b32 v45, v183
	ds_write_b32 v46, v215
	s_waitcnt lgkmcnt(0)
	s_barrier
	s_and_saveexec_b64 s[40:41], s[38:39]
	s_cbranch_execz .LBB0_295
	ds_read_b32 v0, v46
	ds_read_b32 v12, v45
	ds_read_b32 v13, v134
	ds_read_b32 v14, v135
	ds_read_b32 v183, v136
	ds_read_b32 v184, v137
	ds_read_b32 v185, v138
	ds_read_b32 v186, v139
	s_ashr_i32 s0, s2, 3
	v_and_or_b32 v10, s0, -2, v43
	v_ashrrev_i32_e32 v11, 31, v10
	s_mov_b32 s51, s49
	v_lshlrev_b64 v[10:11], 10, v[10:11]
	v_lshl_add_u64 v[10:11], v[10:11], 0, s[50:51]
	v_or_b32_e32 v10, v10, v26
	v_lshlrev_b64 v[10:11], 2, v[10:11]
	s_movk_i32 s23, 0xff7f
	v_readlane_b32 s22, v254, 8
	s_movk_i32 s17, 0x84
	s_mov_b32 s15, 0xfe03f81
	s_movk_i32 s10, 0xc00
	s_waitcnt lgkmcnt(0)
	v_fmac_f32_e32 v14, v0, v13
	v_mul_f32_e32 v0, v12, v13
	v_mul_f32_e32 v0, v0, v183
	v_fmac_f32_e32 v184, v14, v183
	v_fmac_f32_e32 v186, v184, v185
	v_mul_f32_e32 v0, v0, v185
	v_lshl_add_u64 v[12:13], s[34:35], 0, v[10:11]
	v_lshl_add_u64 v[10:11], s[96:97], 0, v[10:11]
	global_store_dword v[12:13], v0, off
	global_store_dword v[10:11], v186, off
	s_branch .LBB0_295
